# ACQ-HOIST: grid barrier - workgroups that wait for their XCD's release issue the agent-scope acquire (buffer_inv sc1) when they start waiting instead of after the release; nothing is loaded through L1
# speedup vs baseline: 1.0109x; 1.0052x over previous
.LBB0_60:
	s_or_b64 exec, exec, s[12:13]
	v_cvt_f32_u32_e32 v5, v3
	s_waitcnt vmcnt(0)
	v_readfirstlane_b32 s0, v4
	v_sub_u32_e32 v4, 0, v3
	v_rcp_iflag_f32_e32 v5, v5
	v_add_u32_e32 v6, s0, v2
	v_mul_f32_e32 v5, 0x4f7ffffe, v5
	v_cvt_u32_f32_e32 v5, v5
	v_mul_lo_u32 v2, v4, v5
	v_mul_hi_u32 v2, v5, v2
	v_add_u32_e32 v2, v5, v2
	v_mul_hi_u32 v2, v6, v2
	v_mul_lo_u32 v4, v2, v3
	v_sub_u32_e32 v4, v6, v4
	v_add_u32_e32 v5, 1, v2
	v_cmp_ge_u32_e32 vcc, v4, v3
	s_nop 1
	v_cndmask_b32_e32 v2, v2, v5, vcc
	v_sub_u32_e32 v5, v4, v3
	v_cndmask_b32_e32 v4, v4, v5, vcc
	v_add_u32_e32 v5, 1, v2
	v_cmp_ge_u32_e32 vcc, v4, v3
	v_add_u32_e32 v4, 1, v6
	s_nop 0
	v_cndmask_b32_e32 v2, v2, v5, vcc
	v_mul_lo_u32 v5, v3, v2
	v_add_u32_e32 v3, v5, v3
	v_cmp_ne_u32_e32 vcc, v4, v3
	s_and_saveexec_b64 s[0:1], vcc
	s_xor_b64 s[10:11], exec, s[0:1]
	s_cbranch_execz .LBB0_74
	buffer_inv sc1
	s_waitcnt lgkmcnt(0)
	v_mov_b32_e32 v1, 0x2000
	global_load_dword v1, v1, s[8:9] offset:1024 sc1
	s_add_u32 s16, s8, 0x2400
	s_addc_u32 s17, s9, 0
	s_waitcnt vmcnt(0)
	v_cmp_eq_u32_e32 vcc, v1, v2
	s_and_saveexec_b64 s[12:13], vcc
	s_cbranch_execz .LBB0_73
	v_readlane_b32 s0, v255, 5
	v_readlane_b32 s1, v255, 6
	s_add_u32 s14, s0, 0x1200
	s_addc_u32 s15, s1, 0
	s_mov_b32 s0, 1
	s_mov_b64 s[18:19], 0
	v_mov_b32_e32 v1, 0
	s_branch .LBB0_64

.LBB0_73:
	s_or_b64 exec, exec, s[12:13]
	s_waitcnt vmcnt(0)
	s_waitcnt vmcnt(0)
